# attention half-step 2: K/V tile prefetch issued at the top of the QK region (8 K-fragment slots + late re-reads)
# speedup vs baseline: 1.0069x; 1.0001x over previous
; __device__ __forceinline__ void partialSM(f32x16& p0, f32x16& p1, float& m_reg, float& mn, float& alpha) {
;     ...
;     const float mnL = -mn * C2;
; #pragma unroll
;     for (int r = 0; r < 16; ++r) p0[r] = fmaf(p0[r], C2, mnL);
; #pragma unroll
;     for (int r = 0; r < 16; ++r) p1[r] = fmaf(p1[r], C2, mnL);
; #pragma unroll
;     for (int r = 0; r < 16; ++r) p0[r] = __builtin_amdgcn_exp2f(p0[r]);
.LBB0_1303:
	v_cndmask_b32_e64 v206, v94, v206, s[6:7]
	v_mul_f32_e32 v207, 0xbe0293ee, v206
	v_fmamk_f32 v94, v146, 0x3e0293ee, v207
	v_fmamk_f32 v82, v82, 0x3e0293ee, v207
	v_fmamk_f32 v83, v83, 0x3e0293ee, v207
	v_fmamk_f32 v95, v147, 0x3e0293ee, v207
	v_fmamk_f32 v96, v148, 0x3e0293ee, v207
	v_fmamk_f32 v97, v149, 0x3e0293ee, v207
	v_fmamk_f32 v87, v87, 0x3e0293ee, v207
	v_fmamk_f32 v88, v88, 0x3e0293ee, v207
	v_fmamk_f32 v89, v89, 0x3e0293ee, v207
	v_fmamk_f32 v90, v90, 0x3e0293ee, v207
	v_fmamk_f32 v91, v91, 0x3e0293ee, v207
	v_fmamk_f32 v92, v92, 0x3e0293ee, v207
	v_fmamk_f32 v93, v93, 0x3e0293ee, v207
	v_fmamk_f32 v79, v79, 0x3e0293ee, v207
	v_fmamk_f32 v80, v80, 0x3e0293ee, v207
	v_fmamk_f32 v81, v81, 0x3e0293ee, v207
	v_exp_f32_e32 v146, v94
	v_exp_f32_e32 v147, v82
	v_exp_f32_e32 v148, v83
	v_exp_f32_e32 v159, v95
	v_exp_f32_e32 v160, v96
	v_exp_f32_e32 v161, v97
	v_exp_f32_e32 v149, v87
	v_exp_f32_e32 v158, v88
	v_exp_f32_e32 v150, v89
	v_exp_f32_e32 v151, v90
	v_exp_f32_e32 v155, v91
	v_exp_f32_e32 v157, v92
	v_exp_f32_e32 v152, v93
	v_exp_f32_e32 v153, v79
	v_exp_f32_e32 v154, v80
	v_exp_f32_e32 v156, v81
	v_fmamk_f32 v210, v71, 0x3e0293ee, v207
	v_fmamk_f32 v209, v78, 0x3e0293ee, v207
	v_fmamk_f32 v217, v66, 0x3e0293ee, v207
	v_fmamk_f32 v218, v67, 0x3e0293ee, v207
	v_fmamk_f32 v219, v68, 0x3e0293ee, v207
	v_fmamk_f32 v220, v69, 0x3e0293ee, v207
	v_fmamk_f32 v221, v70, 0x3e0293ee, v207
	v_fmamk_f32 v211, v72, 0x3e0293ee, v207
	v_fmamk_f32 v212, v84, 0x3e0293ee, v207
	v_fmamk_f32 v213, v85, 0x3e0293ee, v207
	v_fmamk_f32 v214, v86, 0x3e0293ee, v207
	v_fmamk_f32 v215, v76, 0x3e0293ee, v207
	v_fmamk_f32 v216, v77, 0x3e0293ee, v207
	v_fmamk_f32 v222, v73, 0x3e0293ee, v207
	v_fmamk_f32 v223, v74, 0x3e0293ee, v207
	v_fmac_f32_e32 v207, 0x3e0293ee, v75
	s_waitcnt lgkmcnt(0)
	s_barrier
	global_load_dwordx2 v[228:229], v179, s[68:69]
	s_add_i32 s98, s82, 2
	s_cmp_gt_u32 s98, s81
	s_cbranch_scc1 .Lp5_a2
	v_add_co_u32_e32 v130, vcc, 0x60000, v194
	s_nop 1
	v_addc_co_u32_e32 v131, vcc, 0, v195, vcc
	v_add_co_u32_e32 v134, vcc, 0x70000, v194
	s_nop 1
	v_addc_co_u32_e32 v135, vcc, 0, v195, vcc
	v_add_co_u32_e32 v138, vcc, 0x60000, v192
	global_load_dwordx4 v[130:133], v[130:131], off
	s_nop 0
	global_load_dwordx4 v[134:137], v[134:135], off
	v_addc_co_u32_e32 v139, vcc, 0, v193, vcc
	v_add_co_u32_e32 v142, vcc, 0x70000, v192
	s_nop 1
	v_addc_co_u32_e32 v143, vcc, 0, v193, vcc
	global_load_dwordx4 v[138:141], v[138:139], off
	s_nop 0
	global_load_dwordx4 v[142:145], v[142:143], off
; __device__ __forceinline__ void finishSM(f32x16& p0, f32x16& p1, float alpha, float& l_reg, bf16x8& pa0, bf16x8& pa1, bf16x8& pa2, bf16x8& pa3) {
; #pragma unroll
;     for (int r = 0; r < 16; ++r) p1[r] = __builtin_amdgcn_exp2f(p1[r]);
;     float ps = 0;
; #pragma unroll
;     for (int r = 0; r < 16; ++r) ps += p0[r];
; #pragma unroll
;     for (int r = 0; r < 16; ++r) ps += p1[r];
;     { auto rr = __builtin_amdgcn_permlane32_swap(__float_as_uint(ps), __float_as_uint(ps), false, false);
;       ps = __uint_as_float(rr[0]) + __uint_as_float(rr[1]); }
;     l_reg = l_reg * alpha + ps;
;     ...
;     PK4(p0, 0, pa0); PK4(p0, 8, pa1); PK4(p1, 0, pa2); PK4(p1, 8, pa3);
;     ...
; }
; template <int KB>
; __device__ __forceinline__ void qkt(f32x16& p0, f32x16& p1, const char* K_lds, int r32, int hi, const bf16x8* qr) {
;     p0 = f32x16{}; p1 = f32x16{};
;     const char* kb[4];
; #pragma unroll
;     for (int dd = 0; dd < 4; ++dd) kb[dd] = K_lds + KB * SHM_K + KSWZ(r32, (dd * 16 + hi * 8) * 2);
; #pragma unroll
;     for (int d0 = 0; d0 < 8; ++d0) { const char* a = kb[d0 & 3] + (d0 >> 2) * 128;
;         bf16x8 b0 = *reinterpret_cast<const bf16x8*>(a);
;         bf16x8 b1 = *reinterpret_cast<const bf16x8*>(a + 32 * 256);
;         p0 = __builtin_amdgcn_mfma_f32_32x32x16_bf16(b0, qr[d0], p0, 0, 0, 0);
;         p1 = __builtin_amdgcn_mfma_f32_32x32x16_bf16(b1, qr[d0], p1, 0, 0, 0); }
; }
.Lp5_a2:
	ds_read_b128 v[66:69], v199 offset:32768
	ds_read_b128 v[70:73], v199 offset:40960
	ds_read_b128 v[172:175], v200 offset:32768
	ds_read_b128 v[224:227], v200 offset:40960
	ds_read_b128 v[232:235], v201 offset:32768
	ds_read_b128 v[236:239], v201 offset:40960
	ds_read_b128 v[240:243], v202 offset:32768
	ds_read_b128 v[244:247], v202 offset:40960
	v_exp_f32_e32 v211, v211
	v_exp_f32_e32 v212, v212
	s_waitcnt lgkmcnt(7)
	v_mfma_f32_32x32x16_bf16 v[82:97], v[66:69], v[126:129], 0
	v_exp_f32_e32 v213, v213
	v_exp_f32_e32 v214, v214
	v_exp_f32_e32 v215, v215
	s_waitcnt lgkmcnt(6)
	v_mfma_f32_32x32x16_bf16 v[66:81], v[70:73], v[126:129], 0
	v_exp_f32_e32 v216, v216
	v_exp_f32_e32 v207, v207
	s_waitcnt lgkmcnt(5)
	v_mfma_f32_32x32x16_bf16 v[82:97], v[172:175], v[122:125], v[82:97]
	ds_read_b128 v[172:175], v199 offset:32896
	v_exp_f32_e32 v250, v219
	v_exp_f32_e32 v219, v209
	v_add_f32_e32 v209, 0, v146
	v_add_f32_e32 v209, v147, v209
	s_waitcnt lgkmcnt(5)
	v_mfma_f32_32x32x16_bf16 v[66:81], v[224:227], v[122:125], v[66:81]
	ds_read_b128 v[224:227], v199 offset:41088
	v_add_f32_e32 v209, v148, v209
	v_add_f32_e32 v209, v159, v209
	v_add_f32_e32 v209, v160, v209
	v_add_f32_e32 v209, v161, v209
	v_add_f32_e32 v209, v149, v209
	s_waitcnt lgkmcnt(5)
	v_mfma_f32_32x32x16_bf16 v[82:97], v[232:235], v[118:121], v[82:97]
	ds_read_b128 v[232:235], v200 offset:32896
	v_add_f32_e32 v209, v158, v209
	v_add_f32_e32 v209, v150, v209
	v_add_f32_e32 v209, v151, v209
	v_add_f32_e32 v209, v155, v209
	v_add_f32_e32 v209, v157, v209
	s_waitcnt lgkmcnt(5)
	v_mfma_f32_32x32x16_bf16 v[66:81], v[236:239], v[118:121], v[66:81]
	ds_read_b128 v[236:239], v200 offset:41088
	v_exp_f32_e32 v248, v217
	v_add_f32_e32 v209, v152, v209
	v_exp_f32_e32 v249, v218
	s_waitcnt lgkmcnt(5)
	v_mfma_f32_32x32x16_bf16 v[82:97], v[240:243], v[114:117], v[82:97]
	ds_read_b128 v[240:243], v201 offset:32896
	v_add_f32_e32 v209, v153, v209
	v_add_f32_e32 v209, v154, v209
	v_exp_f32_e32 v251, v220
	v_add_f32_e32 v209, v156, v209
	s_waitcnt lgkmcnt(5)
	v_mfma_f32_32x32x16_bf16 v[66:81], v[244:247], v[114:117], v[66:81]
	ds_read_b128 v[244:247], v201 offset:41088
	v_exp_f32_e32 v217, v221
	v_add_f32_e32 v209, v248, v209
	v_exp_f32_e32 v218, v210
	s_waitcnt lgkmcnt(5)
	v_mfma_f32_32x32x16_bf16 v[82:97], v[172:175], v[110:113], v[82:97]
	ds_read_b128 v[172:175], v202 offset:32896
	v_add_f32_e32 v209, v249, v209
	v_add_f32_e32 v209, v250, v209
	v_add_f32_e32 v209, v251, v209
	v_add_f32_e32 v209, v217, v209
	v_add_f32_e32 v209, v218, v209
	s_waitcnt lgkmcnt(5)
	v_mfma_f32_32x32x16_bf16 v[66:81], v[224:227], v[110:113], v[66:81]
	ds_read_b128 v[224:227], v202 offset:41088
	v_add_f32_e32 v209, v211, v209
	v_add_f32_e32 v209, v212, v209
	v_add_f32_e32 v209, v213, v209
	v_exp_f32_e32 v220, v222
	s_waitcnt lgkmcnt(5)
	v_mfma_f32_32x32x16_bf16 v[82:97], v[232:235], v[106:109], v[82:97]
	v_add_f32_e32 v209, v214, v209
	v_exp_f32_e32 v221, v223
	v_add_f32_e32 v209, v215, v209
	v_add_f32_e32 v209, v216, v209
	s_waitcnt lgkmcnt(4)
	v_mfma_f32_32x32x16_bf16 v[66:81], v[236:239], v[106:109], v[66:81]
	v_add_f32_e32 v209, v219, v209
	v_add_f32_e32 v209, v220, v209
	v_add_f32_e32 v209, v221, v209
	v_add_f32_e32 v209, v207, v209
	v_mov_b32_e32 v210, v209
	s_waitcnt lgkmcnt(3)
	v_mfma_f32_32x32x16_bf16 v[82:97], v[240:243], v[102:105], v[82:97]
	v_cvt_pk_bf16_f32 v146, v146, v147
	v_cvt_pk_bf16_f32 v147, v148, v159
	v_cvt_pk_bf16_f32 v148, v160, v161
	v_cvt_pk_bf16_f32 v149, v149, v158
	v_cvt_pk_bf16_f32 v150, v150, v151
	s_waitcnt lgkmcnt(2)
	v_mfma_f32_32x32x16_bf16 v[66:81], v[244:247], v[102:105], v[66:81]
	v_cvt_pk_bf16_f32 v151, v155, v157
	v_cvt_pk_bf16_f32 v152, v152, v153
	v_cvt_pk_bf16_f32 v153, v154, v156
	v_cvt_pk_bf16_f32 v154, v248, v249
	v_cvt_pk_bf16_f32 v155, v250, v251
	s_waitcnt lgkmcnt(1)
	v_mfma_f32_32x32x16_bf16 v[82:97], v[172:175], v[98:101], v[82:97]
	v_cvt_pk_bf16_f32 v156, v217, v218
	v_cvt_pk_bf16_f32 v157, v211, v212
	v_cvt_pk_bf16_f32 v158, v213, v214
	v_cvt_pk_bf16_f32 v159, v215, v216
	v_cvt_pk_bf16_f32 v160, v219, v220
	s_waitcnt lgkmcnt(0)
	v_mfma_f32_32x32x16_bf16 v[66:81], v[224:227], v[98:101], v[66:81]
	v_cvt_pk_bf16_f32 v161, v221, v207
	v_permlane32_swap_b32_e32 v209, v210
	v_permlane32_swap_b32_e32 v146, v148
	v_permlane32_swap_b32_e32 v147, v149
	v_permlane32_swap_b32_e32 v150, v152
	v_permlane32_swap_b32_e32 v151, v153
	v_permlane32_swap_b32_e32 v154, v156
	v_permlane32_swap_b32_e32 v155, v157
	v_permlane32_swap_b32_e32 v158, v160
	v_permlane32_swap_b32_e32 v159, v161
	s_add_i32 s82, s82, 2
	s_cmp_le_u32 s82, s81
	s_cselect_b64 s[36:37], -1, 0
	s_cmp_gt_u32 s82, s81
	s_cbranch_scc1 .Lp5_skip_ld

; #define LAS __attribute__((address_space(3)))
; __global__ void __launch_bounds__(NWAVES * 64, 2) hybrid_fwd(Args args) {
;     extern __shared__ __attribute__((aligned(16))) unsigned char lds_raw[];
;     LAS unsigned char* lds = (LAS unsigned char*)lds_raw;
;     volatile LAS unsigned* MISC = (volatile LAS unsigned*)(lds + MISC_OFF);
;     const int tid = threadIdx.x, lane = tid & 63, wave = __builtin_amdgcn_readfirstlane(tid >> 6);
	.amdhsa_kernel _Z10hybrid_fwd4Args
		.amdhsa_group_segment_fixed_size 0
		.amdhsa_private_segment_fixed_size 0
		.amdhsa_kernarg_size 400
		.amdhsa_user_sgpr_count 2
		.amdhsa_user_sgpr_dispatch_ptr 0
		.amdhsa_user_sgpr_queue_ptr 0
		.amdhsa_user_sgpr_kernarg_segment_ptr 1
		.amdhsa_user_sgpr_dispatch_id 0
		.amdhsa_user_sgpr_kernarg_preload_length 0
		.amdhsa_user_sgpr_kernarg_preload_offset 0
		.amdhsa_user_sgpr_private_segment_size 0
		.amdhsa_uses_dynamic_stack 0
		.amdhsa_enable_private_segment 0
		.amdhsa_system_sgpr_workgroup_id_x 1
		.amdhsa_system_sgpr_workgroup_id_y 0
		.amdhsa_system_sgpr_workgroup_id_z 0
		.amdhsa_system_sgpr_workgroup_info 0
		.amdhsa_system_vgpr_workitem_id 0
		.amdhsa_next_free_vgpr 256
		.amdhsa_next_free_sgpr 102
		.amdhsa_accum_offset 256
		.amdhsa_reserve_vcc 1
		.amdhsa_float_round_mode_32 0
		.amdhsa_float_round_mode_16_64 0
		.amdhsa_float_denorm_mode_32 3
		.amdhsa_float_denorm_mode_16_64 3
		.amdhsa_dx10_clamp 1
		.amdhsa_ieee_mode 1
		.amdhsa_fp16_overflow 0
		.amdhsa_tg_split 0
		.amdhsa_exception_fp_ieee_invalid_op 0
		.amdhsa_exception_fp_denorm_src 0
		.amdhsa_exception_fp_ieee_div_zero 0
		.amdhsa_exception_fp_ieee_overflow 0
		.amdhsa_exception_fp_ieee_underflow 0
		.amdhsa_exception_fp_ieee_inexact 0
		.amdhsa_exception_int_div_zero 0
	.end_amdhsa_kernel

; __global__ void __launch_bounds__(NWAVES * 64, 2) hybrid_fwd(Args args) {
;     extern __shared__ __attribute__((aligned(16))) unsigned char lds_raw[];
amdhsa.kernels:
  - .agpr_count:     0
    .args:
      - .offset:         0
        .size:           144
        .value_kind:     by_value
      - .offset:         144
        .size:           4
        .value_kind:     hidden_block_count_x
      - .offset:         148
        .size:           4
        .value_kind:     hidden_block_count_y
      - .offset:         152
        .size:           4
        .value_kind:     hidden_block_count_z
      - .offset:         156
        .size:           2
        .value_kind:     hidden_group_size_x
      - .offset:         158
        .size:           2
        .value_kind:     hidden_group_size_y
      - .offset:         160
        .size:           2
        .value_kind:     hidden_group_size_z
      - .offset:         162
        .size:           2
        .value_kind:     hidden_remainder_x
      - .offset:         164
        .size:           2
        .value_kind:     hidden_remainder_y
      - .offset:         166
        .size:           2
        .value_kind:     hidden_remainder_z
      - .offset:         184
        .size:           8
        .value_kind:     hidden_global_offset_x
      - .offset:         192
        .size:           8
        .value_kind:     hidden_global_offset_y
      - .offset:         200
        .size:           8
        .value_kind:     hidden_global_offset_z
      - .offset:         208
        .size:           2
        .value_kind:     hidden_grid_dims
      - .offset:         264
        .size:           4
        .value_kind:     hidden_dynamic_lds_size
    .group_segment_fixed_size: 0
    .kernarg_segment_align: 8
    .kernarg_segment_size: 400
    .language:       OpenCL C
    .language_version:
      - 2
      - 0
    .max_flat_workgroup_size: 512
    .name:           _Z10hybrid_fwd4Args
    .private_segment_fixed_size: 0
    .sgpr_count:     108
    .sgpr_spill_count: 34
    .symbol:         _Z10hybrid_fwd4Args.kd
    .uniform_work_group_size: 1
    .uses_dynamic_stack: false
    .vgpr_count:     256
    .vgpr_spill_count: 0
    .wavefront_size: 64
